# NSA selected loop stripped of per-step overhead: SGPR-base K/V DMAs with constant lane offsets (no 64-bit VALU pointer math, no M0 nops), ones operand kept in registers, running selection-mask word
# baseline (speedup 1.0000x reference)
; DI void st_reset(AttnSt& st) {
; #pragma unroll
;   for (int h = 0; h < 2; ++h) {
;     st.m[h] = -1e30f;
;     st.l[h] = 0.f;
;     st.L[h] = f32x4{0.f, 0.f, 0.f, 0.f};
; #pragma unroll
;     for (int dt = 0; dt < 4; ++dt) st.O[h][dt] = f32x4{0.f, 0.f, 0.f, 0.f};
;   }
; }
; template <bool FX>
; DI void nsa_tile(const Params& p, int b, int g, int tile, bf16_t* lds, const float CL) {
;     ...
;   for (int hp = 0; hp < 2; ++hp) {
; #pragma unroll
;     for (int hh = 0; hh < 2; ++hh)
; #pragma unroll
;       for (int ks = 0; ks < 2; ++ks) qf[hh][ks] = *(const bf16x8*)(ztok + C_Q + g * 256 + (hp * 2 + hh) * 64 + ks * 32 + quad * 8);
;     st_reset(st);
;     {
;       const bf16_t* kb = zb + C_KS + g * 64;
;       tile64_gload(tid, rk0, rk1, kb, ZS);
;       tile64_gload(tid, rv0, rv1, vsT, TS);
;       for (int s = 0; s <= cur; ++s) {
;         __syncthreads();
;         tile64_sstore(tid, Ks, rk0, rk1);
;         tile64_sstore(tid, Vs, rv0, rv1);
;         __syncthreads();
;         if (s < cur) {
;           tile64_gload(tid, rk0, rk1, kb + (size_t)(s + 1) * 64 * ZS, ZS);
;           tile64_gload(tid, rv0, rv1, vsT + (s + 1) * 64, TS);
.LBB0_665:
	s_lshl_b32 s28, s6, 8
	v_lshl_add_u64 v[14:15], v[116:117], 0, s[28:29]
	global_load_dwordx4 v[2:5], v[14:15], off
	global_load_dwordx4 v[6:9], v[14:15], off offset:64
	global_load_dwordx4 v[10:13], v[14:15], off offset:128
	s_nop 0
	global_load_dwordx4 v[14:17], v[14:15], off offset:192
	s_nop 0
	v_and_b32_e32 v202, 7, v196
	v_bfe_u32 v218, v196, 4, 3
	v_xor_b32_e32 v202, v202, v218
	v_lshlrev_b32_e32 v202, 4, v202
	v_mov_b32_e32 v203, 0
	v_sub_u32_e32 v218, v202, v0
	v_ashrrev_i32_e32 v219, 31, v218
	v_readfirstlane_b32 s77, v196
	s_lshr_b32 s76, s77, 8
	s_lshl_b32 s76, s76, 16
	s_bfe_u32 s77, s77, 0x20006
	s_lshl_b32 s77, s77, 10
	s_or_b32 s76, s76, s77
	s_or_b32 s76, s76, 0xc000
	s_movk_i32 s78, 0x600
	s_mov_b32 s79, 0
	v_lshl_add_u64 v[58:59], v[132:133], 0, v[218:219]
	v_lshl_add_u64 v[60:61], v[136:137], 0, v[218:219]
	v_lshl_add_u64 v[62:63], v[140:141], 0, v[218:219]
	v_lshl_add_u64 v[64:65], v[144:145], 0, v[218:219]
	v_lshl_add_u64 v[58:59], v[58:59], 0, s[78:79]
	v_lshl_add_u64 v[60:61], v[60:61], 0, s[78:79]
	s_mov_b32 m0, s76
	s_nop 0
	global_load_lds_dwordx4 v[58:59], off
	s_add_u32 m0, s76, 0x1000
	s_nop 0
	global_load_lds_dwordx4 v[60:61], off
	s_add_u32 m0, s76, 0x2000
	s_nop 0
	global_load_lds_dwordx4 v[62:63], off
	s_add_u32 m0, s76, 0x3000
	s_nop 0
	global_load_lds_dwordx4 v[64:65], off
	s_xor_b32 s76, s76, 0xc000
	v_mov_b32_e32 v54, v1
	v_mov_b32_e32 v55, v1
	v_mov_b32_e32 v56, v1
	v_mov_b32_e32 v57, v1
	v_mov_b64_e32 v[46:47], v[54:55]
	v_mov_b64_e32 v[50:51], v[54:55]
	v_mov_b64_e32 v[42:43], v[54:55]
	v_mov_b64_e32 v[38:39], v[54:55]
	v_mov_b64_e32 v[34:35], v[54:55]
	v_mov_b64_e32 v[30:31], v[54:55]
	v_mov_b64_e32 v[26:27], v[54:55]
	v_mov_b64_e32 v[22:23], v[54:55]
	v_mov_b64_e32 v[18:19], v[54:55]
	s_xor_b64 s[36:37], s[2:3], -1
	s_lshl_b32 s7, s6, 7
	s_mov_b32 s28, 64
	s_mov_b32 s68, -1
	v_mov_b32_e32 v187, v185
	v_lshl_add_u64 v[158:159], v[156:157], 0, v[218:219]
	v_lshl_add_u64 v[160:161], v[154:155], 0, v[218:219]
	v_mov_b64_e32 v[48:49], v[56:57]
	v_mov_b64_e32 v[52:53], v[56:57]
	v_mov_b64_e32 v[44:45], v[56:57]
	v_mov_b64_e32 v[40:41], v[56:57]
	v_mov_b64_e32 v[36:37], v[56:57]
	v_mov_b64_e32 v[32:33], v[56:57]
	v_mov_b64_e32 v[28:29], v[56:57]
	v_mov_b64_e32 v[24:25], v[56:57]
	v_mov_b64_e32 v[20:21], v[56:57]
	v_readfirstlane_b32 s80, v158
	v_readfirstlane_b32 s81, v159
	s_sub_u32 s80, s80, 0x40000000
	s_subb_u32 s81, s81, 0
	v_subrev_u32_e32 v62, s80, v158
	v_subrev_u32_e32 v63, s80, v160
	s_lshl_b64 s[2:3], s[28:29], 1
	s_add_u32 s2, s12, s2
	s_addc_u32 s3, s13, s3
	v_lshl_add_u64 v[66:67], v[138:139], 1, s[2:3]
	v_lshl_add_u64 v[68:69], v[142:143], 1, s[2:3]
	v_lshl_add_u64 v[66:67], v[66:67], 0, v[202:203]
	v_lshl_add_u64 v[70:71], v[68:69], 0, v[202:203]
	v_readfirstlane_b32 s82, v66
	v_readfirstlane_b32 s83, v67
	s_sub_u32 s82, s82, 0x40000000
	s_subb_u32 s83, s83, 0
	v_subrev_u32_e32 v64, s82, v66
	v_subrev_u32_e32 v65, s82, v70
	v_mov_b32_e32 v58, s8
	v_mov_b32_e32 v59, s8
	v_mov_b32_e32 v60, s8
	v_mov_b32_e32 v61, s8
	s_branch .LBB0_668_p1
; template <int MODE, bool FX>
; DI void attn_compute(const int lane, const bf16_t* Ks, const bf16_t* Vs, const bf16x8 (&qf)[2][2], AttnSt& st, const float (&invl)[2],
;                      int lo, int hi, float (&impA)[4], float (&impE)[4], const float CL) {
;     ...
;   if (__all(full || none)) {
;     constexpr float L2E = 1.4426950408889634f;
; #pragma unroll
;     for (int hh = 0; hh < 2; ++hh) {
;       float mL;
;       float il = 1.f;
;       if (FX) {
;         mL = full ? CL : 1e30f;
;         if (MODE == 1) il = invl[hh];
;       } else if (MODE != 1) {
;         float mx = -1e30f;
; #pragma unroll
;         for (int kt = 0; kt < 4; ++kt)
; #pragma unroll
;           for (int j = 0; j < 4; ++j) mx = fmaxf(mx, S[kt][hh][j]);
;         mx = full ? mx : -1e30f;
;         mx = fmaxf(mx, shx(mx, 16, lane));
;         mx = fmaxf(mx, shx(mx, 32, lane));
;         const float m_new = fmaxf(st.m[hh], mx);
;         const float alpha = __expf(st.m[hh] - m_new);
;         st.m[hh] = m_new;
;         st.l[hh] *= alpha;
;         if (MODE == 2) {
; #pragma unroll
;           for (int dt = 0; dt < 4; ++dt) st.O[hh][dt] *= alpha;
;         }
;         mL = full ? m_new * L2E : 1e30f;
;       } else {
;         mL = full ? st.m[hh] * L2E : 1e30f;
;         il = invl[hh];
;       }
;       float rs = 0.f;
; #pragma unroll
;       for (int kt = 0; kt < 4; ++kt) {
;         float a = 0.f;
; #pragma unroll
;         for (int j = 0; j < 4; ++j) {
;           float pv = __builtin_amdgcn_exp2f(fmaf(S[kt][hh][j], L2E, -mL));
;           if (MODE == 1) pv *= il;
;           S[kt][hh][j] = pv;
;           a += pv;
;         }
;         rs += a;
;         if (MODE == 1) {
;           impA[kt] += a;
;           impE[kt] += S[kt][hh][3];
;         }
;       }
;       if (MODE != 1 && !(FX && MODE == 2)) st.l[hh] += rs;
;       if (MODE != 0) {
; #pragma unroll
;         for (int c = 0; c < 2; ++c)
;           pf[hh][c] = mk8(pack2(S[2 * c][hh][0], S[2 * c][hh][1]), pack2(S[2 * c][hh][2], S[2 * c][hh][3]),
;                           pack2(S[2 * c + 1][hh][0], S[2 * c + 1][hh][1]), pack2(S[2 * c + 1][hh][2], S[2 * c + 1][hh][3]));
;       }
;     }
;     ...
;   if (MODE != 0) {
; #pragma unroll
;     for (int dt = 0; dt < 4; ++dt) {
;       const int row = dt * 16 + col;
;       const int sw = (row >> 1) & 7;
; #pragma unroll
;       for (int c = 0; c < 2; ++c) {
.Lnsa_fast_p1:
	s_waitcnt lgkmcnt(7)
	v_mfma_f32_16x16x32_bf16 v[98:101], v[220:223], v[2:5], 0
	s_waitcnt lgkmcnt(6)
	v_mfma_f32_16x16x32_bf16 v[106:109], v[224:227], v[2:5], 0
	s_waitcnt lgkmcnt(5)
	v_mfma_f32_16x16x32_bf16 v[102:105], v[228:231], v[2:5], 0
	s_waitcnt lgkmcnt(4)
	v_mfma_f32_16x16x32_bf16 v[110:113], v[232:235], v[2:5], 0
	s_waitcnt lgkmcnt(3)
	v_mfma_f32_16x16x32_bf16 v[98:101], v[236:239], v[6:9], v[98:101]
	s_waitcnt lgkmcnt(2)
	v_mfma_f32_16x16x32_bf16 v[106:109], v[240:243], v[6:9], v[106:109]
	s_waitcnt lgkmcnt(1)
	v_mfma_f32_16x16x32_bf16 v[102:105], v[244:247], v[6:9], v[102:105]
	s_waitcnt lgkmcnt(0)
	v_mfma_f32_16x16x32_bf16 v[110:113], v[198:201], v[6:9], v[110:113]
	v_cmp_lt_i32_e32 vcc, 62, v215
	v_mfma_f32_16x16x32_bf16 v[90:93], v[220:223], v[10:13], 0
	v_mfma_f32_16x16x32_bf16 v[94:97], v[224:227], v[10:13], 0
	v_cndmask_b32_e32 v217, v197, v205, vcc
	v_mfma_f32_16x16x32_bf16 v[82:85], v[228:231], v[10:13], 0
	v_mfma_f32_16x16x32_bf16 v[86:89], v[232:235], v[10:13], 0
	v_fmamk_f32 v74, v98, 0x3fb8aa3b, v217
	v_fmamk_f32 v75, v99, 0x3fb8aa3b, v217
	v_mfma_f32_16x16x32_bf16 v[90:93], v[236:239], v[14:17], v[90:93]
	v_fmamk_f32 v76, v100, 0x3fb8aa3b, v217
	v_fmamk_f32 v77, v101, 0x3fb8aa3b, v217
	v_mfma_f32_16x16x32_bf16 v[94:97], v[240:243], v[14:17], v[94:97]
	v_fmamk_f32 v78, v106, 0x3fb8aa3b, v217
	v_fmamk_f32 v79, v107, 0x3fb8aa3b, v217
	v_mfma_f32_16x16x32_bf16 v[82:85], v[244:247], v[14:17], v[82:85]
	v_fmamk_f32 v80, v108, 0x3fb8aa3b, v217
	v_fmamk_f32 v81, v109, 0x3fb8aa3b, v217
	v_mfma_f32_16x16x32_bf16 v[86:89], v[198:201], v[14:17], v[86:89]
	ds_read_b64 v[220:221], v207 offset:57344
	v_fmamk_f32 v164, v102, 0x3fb8aa3b, v217
	ds_read_b64 v[222:223], v208 offset:57344
	v_fmamk_f32 v165, v103, 0x3fb8aa3b, v217
	ds_read_b64 v[224:225], v209 offset:57344
	v_fmamk_f32 v166, v104, 0x3fb8aa3b, v217
	ds_read_b64 v[226:227], v210 offset:57344
	v_fmamk_f32 v167, v105, 0x3fb8aa3b, v217
	ds_read_b64 v[228:229], v207 offset:59392
	v_fmamk_f32 v168, v110, 0x3fb8aa3b, v217
	ds_read_b64 v[230:231], v208 offset:59392
	v_fmamk_f32 v169, v111, 0x3fb8aa3b, v217
	ds_read_b64 v[232:233], v209 offset:59392
	v_fmamk_f32 v170, v112, 0x3fb8aa3b, v217
	ds_read_b64 v[234:235], v210 offset:59392
	v_fmamk_f32 v171, v113, 0x3fb8aa3b, v217
	ds_read_b64 v[236:237], v207 offset:61440
	v_exp_f32_e32 v74, v74
	ds_read_b64 v[238:239], v208 offset:61440
	v_exp_f32_e32 v75, v75
	ds_read_b64 v[240:241], v209 offset:61440
	v_exp_f32_e32 v76, v76
	ds_read_b64 v[242:243], v210 offset:61440
	v_exp_f32_e32 v77, v77
	ds_read_b64 v[244:245], v211 offset:57344
	v_exp_f32_e32 v78, v78
	ds_read_b64 v[246:247], v212 offset:57344
	v_exp_f32_e32 v79, v79
	ds_read_b64 v[198:199], v213 offset:57344
	v_exp_f32_e32 v80, v80
	ds_read_b64 v[200:201], v214 offset:57344
	v_exp_f32_e32 v81, v81
	v_exp_f32_e32 v164, v164
	v_exp_f32_e32 v165, v165
	v_exp_f32_e32 v166, v166
	v_exp_f32_e32 v167, v167
	v_exp_f32_e32 v168, v168
	v_exp_f32_e32 v169, v169
	v_exp_f32_e32 v170, v170
	v_exp_f32_e32 v171, v171
	v_cvt_pk_bf16_f32 v74, v74, v75
	v_cvt_pk_bf16_f32 v75, v76, v77
	v_cvt_pk_bf16_f32 v76, v78, v79
	v_cvt_pk_bf16_f32 v77, v80, v81
	v_cvt_pk_bf16_f32 v78, v164, v165
	v_cvt_pk_bf16_f32 v79, v166, v167
	v_cvt_pk_bf16_f32 v80, v168, v169
	v_cvt_pk_bf16_f32 v81, v170, v171
	s_waitcnt lgkmcnt(0)
	v_fmamk_f32 v164, v90, 0x3fb8aa3b, v217
	v_fmamk_f32 v165, v91, 0x3fb8aa3b, v217
	v_fmamk_f32 v166, v92, 0x3fb8aa3b, v217
	v_mfma_f32_16x16x32_bf16 v[50:53], v[220:223], v[74:77], v[50:53]
	v_fmamk_f32 v167, v93, 0x3fb8aa3b, v217
	v_mfma_f32_16x16x32_bf16 v[42:45], v[228:231], v[74:77], v[42:45]
	v_fmamk_f32 v168, v94, 0x3fb8aa3b, v217
	v_fmamk_f32 v169, v95, 0x3fb8aa3b, v217
	v_mfma_f32_16x16x32_bf16 v[38:41], v[236:239], v[74:77], v[38:41]
	v_fmamk_f32 v170, v96, 0x3fb8aa3b, v217
	v_fmamk_f32 v171, v97, 0x3fb8aa3b, v217
	v_fmamk_f32 v172, v82, 0x3fb8aa3b, v217
	v_fmamk_f32 v173, v83, 0x3fb8aa3b, v217
	v_mfma_f32_16x16x32_bf16 v[34:37], v[244:247], v[74:77], v[34:37]
	v_fmamk_f32 v174, v84, 0x3fb8aa3b, v217
	v_fmamk_f32 v175, v85, 0x3fb8aa3b, v217
	v_fmamk_f32 v176, v86, 0x3fb8aa3b, v217
	v_fmamk_f32 v177, v87, 0x3fb8aa3b, v217
	v_mfma_f32_16x16x32_bf16 v[50:53], v[224:227], v[78:81], v[50:53]
	v_fmamk_f32 v178, v88, 0x3fb8aa3b, v217
	v_fmamk_f32 v179, v89, 0x3fb8aa3b, v217
	v_exp_f32_e32 v164, v164
	v_exp_f32_e32 v165, v165
	v_mfma_f32_16x16x32_bf16 v[42:45], v[232:235], v[78:81], v[42:45]
	v_exp_f32_e32 v166, v166
	v_exp_f32_e32 v167, v167
	v_exp_f32_e32 v168, v168
	v_exp_f32_e32 v169, v169
	v_mfma_f32_16x16x32_bf16 v[38:41], v[240:243], v[78:81], v[38:41]
	v_exp_f32_e32 v170, v170
	v_exp_f32_e32 v171, v171
	v_exp_f32_e32 v172, v172
	v_exp_f32_e32 v173, v173
	v_mfma_f32_16x16x32_bf16 v[34:37], v[198:201], v[78:81], v[34:37]
	v_exp_f32_e32 v174, v174
	v_exp_f32_e32 v175, v175
	v_exp_f32_e32 v176, v176
	v_exp_f32_e32 v177, v177
	v_mfma_f32_16x16x32_bf16 v[54:57], v[58:61], v[74:77], v[54:57]
	v_exp_f32_e32 v178, v178
	v_exp_f32_e32 v179, v179
	v_cvt_pk_bf16_f32 v82, v164, v165
	v_cvt_pk_bf16_f32 v83, v166, v167
	v_mfma_f32_16x16x32_bf16 v[54:57], v[58:61], v[78:81], v[54:57]
	v_cvt_pk_bf16_f32 v84, v168, v169
	v_cvt_pk_bf16_f32 v85, v170, v171
	v_cvt_pk_bf16_f32 v86, v172, v173
	v_cvt_pk_bf16_f32 v87, v174, v175
	v_cvt_pk_bf16_f32 v88, v176, v177
	v_cvt_pk_bf16_f32 v89, v178, v179
	s_nop 1
	v_mfma_f32_16x16x32_bf16 v[30:33], v[220:223], v[82:85], v[30:33]
	v_mfma_f32_16x16x32_bf16 v[26:29], v[228:231], v[82:85], v[26:29]
	v_mfma_f32_16x16x32_bf16 v[22:25], v[236:239], v[82:85], v[22:25]
	v_mfma_f32_16x16x32_bf16 v[18:21], v[244:247], v[82:85], v[18:21]
	v_mfma_f32_16x16x32_bf16 v[30:33], v[224:227], v[86:89], v[30:33]
	v_mfma_f32_16x16x32_bf16 v[26:29], v[232:235], v[86:89], v[26:29]
	v_mfma_f32_16x16x32_bf16 v[22:25], v[240:243], v[86:89], v[22:25]
	v_mfma_f32_16x16x32_bf16 v[18:21], v[198:201], v[86:89], v[18:21]
	v_mfma_f32_16x16x32_bf16 v[46:49], v[58:61], v[82:85], v[46:49]
	v_mfma_f32_16x16x32_bf16 v[46:49], v[58:61], v[86:89], v[46:49]
	s_branch .LBB0_667_p1

; template <bool FX>
; DI void nsa_tile(const Params& p, int b, int g, int tile, bf16_t* lds, const float CL) {
;     ...
;       for (int s = 0; s <= cur; ++s) {
;         __syncthreads();
;         tile64_sstore(tid, Ks, rk0, rk1);
;         tile64_sstore(tid, Vs, rv0, rv1);
;         __syncthreads();
;         if (s < cur) {
;           tile64_gload(tid, rk0, rk1, kb + (size_t)(s + 1) * 64 * ZS, ZS);
;           tile64_gload(tid, rv0, rv1, vsT + (s + 1) * 64, TS);
;         }
;         uint32_t wsel = (s < 32) ? sw0 : (s < 64) ? sw1 : (s < 96) ? sw2 : sw3;
;         bool sel = (wsel >> (s & 31)) & 1u;
;         int hi = sel ? (tok - s * 64) : -1;
;         if (__any(hi >= 0)) attn_compute<2, FX>(lane, Ks, Vs, qf, st, invl, 0, hi, dA, dE, CL);
.LBB0_667_p1:
	s_add_i32 s28, s28, 64
	s_cmp_eq_u32 s25, s68
	v_subrev_u32_e32 v187, 64, v187
	s_cbranch_scc1 .LBB0_675
	s_branch .LBB0_668
.LBB0_668_p1:
	s_add_i32 s68, s68, 1
	s_and_b32 s87, s68, 31
	s_cmp_lg_u32 s87, 0
	s_cbranch_scc1 .Lnsa_mk_p1
	s_cmp_lt_u32 s68, 32
	s_cselect_b64 vcc, -1, 0
	s_cmp_lt_u32 s68, 64
	s_cselect_b64 s[2:3], -1, 0
	s_cmpk_lt_u32 s68, 0x60
	s_cselect_b64 s[4:5], -1, 0
	v_cndmask_b32_e64 v72, v183, v182, s[4:5]
	v_cndmask_b32_e64 v72, v72, v181, s[2:3]
	v_cndmask_b32_e32 v72, v72, v180, vcc
.Lnsa_mk_p1:
	v_and_b32_e32 v74, 1, v72
	v_lshrrev_b32_e32 v72, 1, v72
	v_cmp_eq_u32_e32 vcc, 1, v74
	s_nop 1
	v_cndmask_b32_e32 v215, -1, v187, vcc
	v_cmp_lt_i32_e32 vcc, -1, v215
	s_cmp_ge_u32 s68, s25
	s_waitcnt vmcnt(0)
	s_barrier
	s_cbranch_scc1 .LBB0_670_p1
	s_mov_b32 m0, s76
	s_add_u32 s86, s76, 0x1000
	global_load_lds_dwordx4 v62, s[80:81]
	s_mov_b32 m0, s86
	s_add_u32 s86, s76, 0x2000
	global_load_lds_dwordx4 v63, s[80:81]
	s_mov_b32 m0, s86
	s_add_u32 s86, s76, 0x3000
	global_load_lds_dwordx4 v64, s[82:83]
	s_mov_b32 m0, s86
	s_add_u32 s80, s80, s22
	global_load_lds_dwordx4 v65, s[82:83]
	s_addc_u32 s81, s81, s23
	s_add_u32 s82, s82, 0x80
	s_addc_u32 s83, s83, 0
	s_xor_b32 s76, s76, 0xc000
